# code placement: GDN chunk loop head aligned to 64 bytes (.p2align 6)
# baseline (speedup 1.0000x reference)
; #define LAS __attribute__((address_space(3)))
; __device__ __forceinline__ unsigned pk2(float lo, float hi) { const f32v2_t f = {lo, hi}; const bf16v2_t b = __builtin_convertvector(f, bf16v2_t); return __builtin_bit_cast(unsigned, b); }
; #define WAVE_SYNC() do { asm volatile("s_waitcnt lgkmcnt(0)" ::: "memory"); __builtin_amdgcn_wave_barrier(); asm volatile("" ::: "memory"); } while (0)
; #define MFMA16(a, b, c) __builtin_amdgcn_mfma_f32_16x16x32_bf16((a), (b), (c), 0, 0, 0)
; template <int MODE>
; __device__ NOINL void chain_item(const LAS Params* lp, int l, int item, bool ctx_out, LAS unsigned char* lds) {
;     ...
; #pragma unroll
;         for (int dk = 0; dk < NDK; ++dk) { u32x2 pk; pk.x = pk2(Sacc[dk][0], Sacc[dk][1]); pk.y = pk2(Sacc[dk][2], Sacc[dk][3]); *(LAS u32x2*)(ST + fr * 136 + 16 * dk + 4 * fq) = pk; }
;         WAVE_SYNC();
;         f32x4 qs[4], ksm[4];
; #pragma unroll
;         for (int ct = 0; ct < 4; ++ct) { qs[ct] = (f32x4){0.f, 0.f, 0.f, 0.f}; ksm[ct] = (f32x4){0.f, 0.f, 0.f, 0.f}; }
; #pragma unroll
;         for (int ks = 0; ks < NKS; ++ks) {
;             const bf16x8 Bf = *(const LAS bf16x8*)(ST + fr * 136 + ks * 32 + fq * 8);
; #pragma unroll
;             for (int ct = 0; ct < 4; ++ct) {
;                 const bf16x8 Aq = *(const LAS bf16x8*)(Qs + (16 * ct + fr) * 136 + kcol + ks * 32 + fq * 8);
;                 qs[ct] = MFMA16(Aq, Bf, qs[ct]);
;                 if (MODE == 0) { const bf16x8 Ak = *(const LAS bf16x8*)(Ks + (16 * ct + fr) * 136 + ks * 32 + fq * 8); ksm[ct] = MFMA16(Ak, Bf, ksm[ct]); }
;             }
;         }
.LBB0_1141:
	s_or_b64 exec, exec, s[62:63]
	ds_write_b16 v178, v68
	v_cvt_pk_bf16_f32 v68, v28, v29
	v_cvt_pk_bf16_f32 v69, v30, v31
	v_cvt_pk_bf16_f32 v70, v40, v41
	v_cvt_pk_bf16_f32 v71, v42, v43
	ds_write2_b64 v113, v[68:69], v[70:71] offset1:4
	v_cvt_pk_bf16_f32 v68, v32, v33
	v_cvt_pk_bf16_f32 v69, v34, v35
	v_cvt_pk_bf16_f32 v70, v36, v37
	v_cvt_pk_bf16_f32 v71, v38, v39
	ds_write2_b64 v113, v[68:69], v[70:71] offset0:8 offset1:12
	v_cvt_pk_bf16_f32 v68, v56, v57
	v_cvt_pk_bf16_f32 v69, v58, v59
	v_cvt_pk_bf16_f32 v70, v52, v53
	v_cvt_pk_bf16_f32 v71, v54, v55
	ds_write2_b64 v113, v[68:69], v[70:71] offset0:16 offset1:20
	v_cvt_pk_bf16_f32 v68, v44, v45
	v_cvt_pk_bf16_f32 v69, v46, v47
	v_cvt_pk_bf16_f32 v70, v48, v49
	v_cvt_pk_bf16_f32 v71, v50, v51
	ds_write2_b64 v113, v[68:69], v[70:71] offset0:24 offset1:28
	s_waitcnt lgkmcnt(0)
	v_add_u32_e32 v119, v113, v154
	ds_read_b128 v[84:87], v119
	ds_read_b128 v[100:103], v179
	ds_read_b128 v[104:107], v179 offset:17408
	ds_read_b128 v[194:197], v179 offset:4352
	ds_read_b128 v[236:239], v179 offset:21760
	ds_read_b128 v[240:243], v179 offset:8704
	ds_read_b128 v[244:247], v179 offset:26112
	ds_read_b128 v[248:251], v179 offset:13056
	v_add_u32_e32 v121, 0x25500, v110
	s_waitcnt lgkmcnt(6)
	v_mfma_f32_16x16x32_bf16 v[96:99], v[100:103], v[84:87], 0
	ds_read_b128 v[100:103], v179 offset:30464
	ds_read_b128 v[88:91], v119 offset:64
	s_add_i32 s5, s4, 4
	s_waitcnt lgkmcnt(7)
	v_mfma_f32_16x16x32_bf16 v[198:201], v[104:107], v[84:87], 0
	ds_read_b128 v[104:107], v179 offset:64
	s_and_b64 s[20:21], vcc, exec
	s_waitcnt lgkmcnt(7)
	v_mfma_f32_16x16x32_bf16 v[92:95], v[194:197], v[84:87], 0
	ds_read_b128 v[194:197], v179 offset:17472
	s_cselect_b32 s5, s1, s5
	s_waitcnt lgkmcnt(7)
	v_mfma_f32_16x16x32_bf16 v[232:235], v[236:239], v[84:87], 0
	ds_read_b128 v[236:239], v179 offset:4416
	s_add_i32 s22, s4, 40
	s_waitcnt lgkmcnt(7)
	v_mfma_f32_16x16x32_bf16 v[80:83], v[240:243], v[84:87], 0
	ds_read_b128 v[240:243], v179 offset:21824
	s_and_b64 s[20:21], vcc, exec
	s_waitcnt lgkmcnt(7)
	v_mfma_f32_16x16x32_bf16 v[72:75], v[244:247], v[84:87], 0
	ds_read_b128 v[244:247], v179 offset:8768
	s_cselect_b32 s20, s1, s22
	s_waitcnt lgkmcnt(7)
	v_mfma_f32_16x16x32_bf16 v[76:79], v[248:251], v[84:87], 0
	ds_read_b128 v[248:251], v179 offset:26176
	s_cmp_lt_u32 s1, 4
	s_waitcnt lgkmcnt(7)
	v_mfma_f32_16x16x32_bf16 v[68:71], v[100:103], v[84:87], 0
	ds_read_b128 v[100:103], v179 offset:13120
	s_cselect_b32 s1, s5, s20
	s_waitcnt lgkmcnt(6)
	v_mfma_f32_16x16x32_bf16 v[96:99], v[104:107], v[88:91], v[96:99]
	ds_read_b128 v[104:107], v179 offset:30528
	ds_read_b128 v[84:87], v119 offset:128
	s_lshl_b32 s5, s1, 6
	s_waitcnt lgkmcnt(7)
	v_mfma_f32_16x16x32_bf16 v[198:201], v[194:197], v[88:91], v[198:201]
	ds_read_b128 v[194:197], v179 offset:128
	s_add_i32 s20, s18, s5
	s_waitcnt lgkmcnt(7)
	v_mfma_f32_16x16x32_bf16 v[92:95], v[236:239], v[88:91], v[92:95]
	ds_read_b128 v[236:239], v179 offset:17536
	s_or_b32 s5, s5, s38
	s_waitcnt lgkmcnt(7)
	v_mfma_f32_16x16x32_bf16 v[232:235], v[240:243], v[88:91], v[232:235]
	ds_read_b128 v[240:243], v179 offset:4480
	s_cmp_lt_u32 s1, 4
	s_waitcnt lgkmcnt(7)
	v_mfma_f32_16x16x32_bf16 v[80:83], v[244:247], v[88:91], v[80:83]
	ds_read_b128 v[244:247], v179 offset:21888
	s_cselect_b32 s1, s5, s20
	s_waitcnt lgkmcnt(7)
	v_mfma_f32_16x16x32_bf16 v[72:75], v[248:251], v[88:91], v[72:75]
	ds_read_b128 v[248:251], v179 offset:8832
	s_mul_hi_i32 s21, s1, s19
	s_waitcnt lgkmcnt(7)
	v_mfma_f32_16x16x32_bf16 v[76:79], v[100:103], v[88:91], v[76:79]
	ds_read_b128 v[100:103], v179 offset:26240
	s_mul_i32 s20, s1, s19
	s_waitcnt lgkmcnt(7)
	v_mfma_f32_16x16x32_bf16 v[68:71], v[104:107], v[88:91], v[68:71]
	ds_read_b128 v[104:107], v179 offset:13184
	v_mov_b32_e32 v123, v1
	s_waitcnt lgkmcnt(6)
	v_mfma_f32_16x16x32_bf16 v[96:99], v[194:197], v[84:87], v[96:99]
	ds_read_b128 v[194:197], v179 offset:30592
	ds_read_b128 v[88:91], v119 offset:192
	v_add_u32_e32 v119, s34, v155
	v_mov_b32_e32 v125, v1
	s_waitcnt lgkmcnt(7)
	v_mfma_f32_16x16x32_bf16 v[198:201], v[236:239], v[84:87], v[198:201]
	ds_read_b128 v[236:239], v179 offset:192
	v_mov_b32_e32 v127, v1
	s_waitcnt lgkmcnt(7)
	v_mfma_f32_16x16x32_bf16 v[92:95], v[240:243], v[84:87], v[92:95]
	ds_read_b128 v[240:243], v179 offset:17600
	v_mov_b32_e32 v129, v1
	s_waitcnt lgkmcnt(7)
	v_mfma_f32_16x16x32_bf16 v[232:235], v[244:247], v[84:87], v[232:235]
	ds_read_b128 v[244:247], v179 offset:4544
	v_mov_b32_e32 v131, v1
	s_waitcnt lgkmcnt(7)
	v_mfma_f32_16x16x32_bf16 v[80:83], v[248:251], v[84:87], v[80:83]
	ds_read_b128 v[248:251], v179 offset:21952
	v_mov_b32_e32 v133, v1
	s_waitcnt lgkmcnt(7)
	v_mfma_f32_16x16x32_bf16 v[72:75], v[100:103], v[84:87], v[72:75]
	ds_read_b128 v[100:103], v179 offset:8896
	v_mov_b32_e32 v135, v1
	s_waitcnt lgkmcnt(7)
	v_mfma_f32_16x16x32_bf16 v[76:79], v[104:107], v[84:87], v[76:79]
	ds_read_b128 v[104:107], v179 offset:26304
	v_mov_b32_e32 v137, v1
	s_waitcnt lgkmcnt(7)
	v_mfma_f32_16x16x32_bf16 v[68:71], v[194:197], v[84:87], v[68:71]
	ds_read_b128 v[194:197], v179 offset:13248
	v_mov_b32_e32 v139, v1
	s_waitcnt lgkmcnt(6)
	v_mfma_f32_16x16x32_bf16 v[96:99], v[236:239], v[88:91], v[96:99]
	ds_read_b128 v[236:239], v179 offset:30656
	v_mov_b32_e32 v141, v1
	s_waitcnt lgkmcnt(6)
	v_mfma_f32_16x16x32_bf16 v[198:201], v[240:243], v[88:91], v[198:201]
	v_mov_b32_e32 v143, v1
	s_waitcnt lgkmcnt(5)
	v_mfma_f32_16x16x32_bf16 v[92:95], v[244:247], v[88:91], v[92:95]
	v_mov_b32_e32 v145, v1
	s_waitcnt lgkmcnt(4)
	v_mfma_f32_16x16x32_bf16 v[232:235], v[248:251], v[88:91], v[232:235]
	v_mov_b32_e32 v147, v1
	s_waitcnt lgkmcnt(3)
; #define LAS __attribute__((address_space(3)))
; __device__ __forceinline__ unsigned pk2(float lo, float hi) { const f32v2_t f = {lo, hi}; const bf16v2_t b = __builtin_convertvector(f, bf16v2_t); return __builtin_bit_cast(unsigned, b); }
; __device__ __forceinline__ float bflo(unsigned u) { return __uint_as_float(u << 16); }
; __device__ __forceinline__ float bfhi(unsigned u) { return __uint_as_float(u & 0xFFFF0000u); }
; #define WAVE_SYNC() do { asm volatile("s_waitcnt lgkmcnt(0)" ::: "memory"); __builtin_amdgcn_wave_barrier(); asm volatile("" ::: "memory"); } while (0)
; #define MFMA16(a, b, c) __builtin_amdgcn_mfma_f32_16x16x32_bf16((a), (b), (c), 0, 0, 0)
; template <int MODE>
; __device__ NOINL void chain_item(const LAS Params* lp, int l, int item, bool ctx_out, LAS unsigned char* lds) {
;     ...
;         if (MODE == 0) {
; #pragma unroll
;             for (int ct = 0; ct < 4; ++ct) {
;                 const u32x2 vv = *(const LAS u32x2*)(VT + (dvrow + fr) * 72 + (((2 * ct + (fq >> 1)) ^ vkey) << 3) + 4 * (fq & 1));
;                 const float v4[4] = {bflo(vv.x), bfhi(vv.x), bflo(vv.y), bfhi(vv.y)};
;                 float r[4];
; #pragma unroll
;                 for (int j = 0; j < 4; ++j) r[j] = bts[16 * ct + 4 * fq + j] * (v4[j] - eg[ct][j] * ksm[ct][j]);
;                 u32x2 pk; pk.x = pk2(r[0], r[1]); pk.y = pk2(r[2], r[3]);
;                 *(LAS u32x2*)(RP + fr * 72 + 16 * ct + 4 * fq) = pk;
;             }
;             WAVE_SYNC();
;             bf16x8 Br[2];
;             Br[0] = *(const LAS bf16x8*)(RP + fr * 72 + fq * 8); Br[1] = *(const LAS bf16x8*)(RP + fr * 72 + 32 + fq * 8);
;             f32x4 vn[4];
; #pragma unroll
;             for (int ct = 0; ct < 4; ++ct) {
;                 vn[ct] = (f32x4){0.f, 0.f, 0.f, 0.f};
; #pragma unroll
;                 for (int ks = 0; ks < 2; ++ks) { const bf16x8 A = *(const LAS bf16x8*)(TT + (16 * ct + fr) * 72 + ks * 32 + fq * 8); vn[ct] = MFMA16(A, Br[ks], vn[ct]); }
;             }
	v_mfma_f32_16x16x32_bf16 v[80:83], v[100:103], v[88:91], v[80:83]
	s_add_i32 s4, s4, -1
	s_waitcnt lgkmcnt(2)
	v_mfma_f32_16x16x32_bf16 v[72:75], v[104:107], v[88:91], v[72:75]
	s_cmp_lg_u32 s0, 36
	s_waitcnt lgkmcnt(1)
	v_mfma_f32_16x16x32_bf16 v[76:79], v[194:197], v[88:91], v[76:79]
	s_mov_b32 s1, s0
	s_waitcnt lgkmcnt(0)
	v_mfma_f32_16x16x32_bf16 v[68:71], v[236:239], v[88:91], v[68:71]
	ds_read_b64 v[88:89], v186 offset:53248
	ds_read_b128 v[104:107], v119 offset:512
	ds_read_b128 v[84:87], v121
	s_waitcnt lgkmcnt(2)
	v_lshlrev_b32_e32 v90, 16, v88
	v_and_b32_e32 v91, 0xffff0000, v88
	v_lshlrev_b32_e32 v88, 16, v89
	v_and_b32_e32 v89, 0xffff0000, v89
	s_waitcnt lgkmcnt(1)
	v_pk_fma_f32 v[90:91], v[198:199], v[104:105], v[90:91] neg_lo:[1,0,0] neg_hi:[1,0,0]
	v_pk_fma_f32 v[88:89], v[200:201], v[106:107], v[88:89] neg_lo:[1,0,0] neg_hi:[1,0,0]
	s_waitcnt lgkmcnt(0)
	v_pk_mul_f32 v[84:85], v[84:85], v[90:91]
	v_pk_mul_f32 v[86:87], v[86:87], v[88:89]
	v_cvt_pk_bf16_f32 v148, v84, v85
	v_cvt_pk_bf16_f32 v149, v86, v87
	ds_read_b128 v[100:103], v119 offset:576
	ds_read_b128 v[88:91], v119 offset:640
	ds_read_b128 v[84:87], v119 offset:704
	ds_write_b64 v158, v[148:149] offset:4352
	ds_read_b64 v[148:149], v187 offset:53248
	ds_read_b128 v[194:197], v121 offset:64
	v_add_u32_e32 v119, v158, v154
	s_waitcnt lgkmcnt(1)
	v_lshlrev_b32_e32 v198, 16, v148
	v_and_b32_e32 v199, 0xffff0000, v148
	v_lshlrev_b32_e32 v148, 16, v149
	v_and_b32_e32 v149, 0xffff0000, v149
	v_pk_fma_f32 v[198:199], v[232:233], v[100:101], v[198:199] neg_lo:[1,0,0] neg_hi:[1,0,0]
	v_pk_fma_f32 v[148:149], v[234:235], v[102:103], v[148:149] neg_lo:[1,0,0] neg_hi:[1,0,0]
	s_waitcnt lgkmcnt(0)
	v_pk_mul_f32 v[194:195], v[194:195], v[198:199]
	v_pk_mul_f32 v[148:149], v[196:197], v[148:149]
	v_cvt_pk_bf16_f32 v194, v194, v195
	v_cvt_pk_bf16_f32 v195, v148, v149
	ds_write_b64 v158, v[194:195] offset:4384
	ds_read_b64 v[148:149], v188 offset:53248
	ds_read_b128 v[194:197], v121 offset:128
	s_waitcnt lgkmcnt(1)
	v_lshlrev_b32_e32 v198, 16, v148
	v_and_b32_e32 v199, 0xffff0000, v148
	v_lshlrev_b32_e32 v148, 16, v149
	v_and_b32_e32 v149, 0xffff0000, v149
	v_pk_fma_f32 v[72:73], v[72:73], v[88:89], v[198:199] neg_lo:[1,0,0] neg_hi:[1,0,0]
	v_pk_fma_f32 v[74:75], v[74:75], v[90:91], v[148:149] neg_lo:[1,0,0] neg_hi:[1,0,0]
	s_waitcnt lgkmcnt(0)
	v_pk_mul_f32 v[72:73], v[194:195], v[72:73]
	v_pk_mul_f32 v[74:75], v[196:197], v[74:75]
	v_cvt_pk_bf16_f32 v72, v72, v73
	v_cvt_pk_bf16_f32 v73, v74, v75
	ds_write_b64 v158, v[72:73] offset:4416
	ds_read_b64 v[72:73], v189 offset:53248
	s_waitcnt lgkmcnt(0)
	v_lshlrev_b32_e32 v148, 16, v72
	v_and_b32_e32 v149, 0xffff0000, v72
	v_lshlrev_b32_e32 v194, 16, v73
	v_and_b32_e32 v195, 0xffff0000, v73
	ds_read_b128 v[72:75], v121 offset:192
	v_pk_fma_f32 v[68:69], v[68:69], v[84:85], v[148:149] neg_lo:[1,0,0] neg_hi:[1,0,0]
	v_pk_fma_f32 v[70:71], v[70:71], v[86:87], v[194:195] neg_lo:[1,0,0] neg_hi:[1,0,0]
	v_add_u32_e32 v121, v159, v157
	v_lshl_add_u64 v[148:149], s[20:21], 1, v[116:117]
	s_waitcnt lgkmcnt(0)
	v_pk_mul_f32 v[68:69], v[72:73], v[68:69]
	v_pk_mul_f32 v[70:71], v[74:75], v[70:71]
	v_cvt_pk_bf16_f32 v68, v68, v69
	v_cvt_pk_bf16_f32 v69, v70, v71
	ds_write_b64 v158, v[68:69] offset:4448
	s_waitcnt lgkmcnt(0)
	ds_read_b128 v[68:71], v119 offset:4352
	ds_read_b128 v[72:75], v119 offset:4416
	ds_read_b128 v[194:197], v121
	ds_read_b128 v[198:201], v121 offset:64
	v_add_u32_e32 v121, v159, v180
	ds_read_b128 v[232:235], v121
	ds_read_b128 v[236:239], v121 offset:64
	ds_read_b128 v[240:243], v121 offset:2304
	ds_read_b128 v[244:247], v121 offset:2368
	ds_read_b128 v[248:251], v121 offset:4608
	s_waitcnt lgkmcnt(6)
	v_mfma_f32_16x16x32_bf16 v[194:197], v[194:197], v[68:71], 0
	s_waitcnt lgkmcnt(5)
	v_mfma_f32_16x16x32_bf16 v[194:197], v[198:201], v[72:75], v[194:197]
	ds_read_b128 v[198:201], v121 offset:4672
	v_add_u32_e32 v121, 0x1000, v158
	s_waitcnt lgkmcnt(5)
	v_mfma_f32_16x16x32_bf16 v[232:235], v[232:235], v[68:71], 0
	s_waitcnt lgkmcnt(4)
	v_mfma_f32_16x16x32_bf16 v[232:235], v[236:239], v[72:75], v[232:235]
	s_waitcnt lgkmcnt(3)
	v_mfma_f32_16x16x32_bf16 v[240:243], v[240:243], v[68:71], 0
	s_waitcnt lgkmcnt(2)
	v_mfma_f32_16x16x32_bf16 v[240:243], v[244:247], v[72:75], v[240:243]
	s_waitcnt lgkmcnt(1)
	v_mfma_f32_16x16x32_bf16 v[248:251], v[248:251], v[68:71], 0
	s_waitcnt lgkmcnt(0)
	v_mfma_f32_16x16x32_bf16 v[248:251], v[198:201], v[72:75], v[248:251]
	v_cvt_pk_bf16_f32 v72, v194, v195
	v_cvt_pk_bf16_f32 v73, v196, v197
	v_cvt_pk_bf16_f32 v74, v232, v233
	v_cvt_pk_bf16_f32 v75, v234, v235
	ds_write2_b64 v121, v[72:73], v[74:75] offset0:32 offset1:36
	v_cvt_pk_bf16_f32 v72, v240, v241
	v_cvt_pk_bf16_f32 v73, v242, v243
	s_nop 1
	v_cvt_pk_bf16_f32 v68, v248, v249
	v_cvt_pk_bf16_f32 v69, v250, v251
	ds_write2_b64 v121, v[72:73], v[68:69] offset0:40 offset1:44
	s_waitcnt lgkmcnt(0)
	s_barrier
; #define LAS __attribute__((address_space(3)))
; __device__ __forceinline__ bf16_t f2bf(float f) { return (bf16_t)(pk2(f, f) & 0xFFFFu); }
; #define MFMA16(a, b, c) __builtin_amdgcn_mfma_f32_16x16x32_bf16((a), (b), (c), 0, 0, 0)
; template <int MODE>
; __device__ NOINL void chain_item(const LAS Params* lp, int l, int item, bool ctx_out, LAS unsigned char* lds) {
;     ...
;             Bv[0] = *(const LAS bf16x8*)(RP + fr * 72 + fq * 8); Bv[1] = *(const LAS bf16x8*)(RP + fr * 72 + 32 + fq * 8);
;         } else {
;             Bv[0] = *(const LAS bf16x8*)(VT + (dvrow + fr) * 72 + ((fq ^ vkey) << 3)); Bv[1] = *(const LAS bf16x8*)(VT + (dvrow + fr) * 72 + (((4 + fq) ^ vkey) << 3));
;         }
;         {
;             typedef __attribute__((address_space(1))) bf16_t gbf16;
;             bf16_t* ob; int ldo;
;             if (MODE == 0) { if (dir == 0) { ob = p.hbuf + 256 + h * 128 + 16 * w; ldo = 1024; } else { ob = p.hyproj + h * 128 + 16 * w; ldo = 768; } }
;             else { if (dir == 0) { ob = p.hbuf + 768 + (h + hh) * 64 + 16 * (w & 3); ldo = 1024; } else { ob = p.hyproj + 512 + (h + hh) * 64 + 16 * (w & 3); ldo = 768; } }
; #pragma unroll
;             for (int ct = 0; ct < 4; ++ct) {
;                 f32x4 acc = {0.f, 0.f, 0.f, 0.f};
; #pragma unroll
;                 for (int ks = 0; ks < 2; ++ks) { const bf16x8 A = *(const LAS bf16x8*)(AT + hh * 4608 + (16 * ct + fr) * 72 + ks * 32 + fq * 8); acc = MFMA16(A, Bv[ks], acc); }
;                 gbf16* og = (gbf16*)ob + (size_t)row0 * ldo + fr;
; #pragma unroll
;                 for (int j = 0; j < 4; ++j) { const int c = 16 * ct + 4 * fq + j, tok = dir ? 63 - c : c; og[tok * ldo] = f2bf(eg[ct][j] * qs[ct][j] + acc[j]); }
;             }
;         }
;         {
;             const float gl = MODE == 0 ? gcs[128 + 63] : __expf(64.f * lg);
; #pragma unroll
;             for (int dk = 0; dk < NDK; ++dk) {
;                 Sacc[dk] = Sacc[dk] * gl;
; #pragma unroll
;                 for (int ks = 0; ks < 2; ++ks) { const bf16x8 A = *(const LAS bf16x8*)(KT + (kcol + 16 * dk + fr) * 72 + (((ks * 4 + fq) ^ (((kcol >> 4) + dk) & 7)) << 3)); Sacc[dk] = MFMA16(A, Bv[ks], Sacc[dk]); }
	ds_read_b128 v[72:75], v119 offset:4352
	ds_read_b128 v[68:71], v119 offset:4416
	v_add_u32_e32 v218, v160, v157
	v_add_u32_e32 v219, v160, v180
	v_mov_b32_e32 v119, v1
	v_mov_b32_e32 v121, v1
	ds_read_b128 v[194:197], v218
	ds_read_b128 v[232:235], v219
	ds_read_b128 v[244:247], v219 offset:2304
	ds_read_b128 v[236:239], v219 offset:4608
	ds_read_b128 v[198:201], v218 offset:64
	ds_read_b128 v[240:243], v219 offset:64
	ds_read_b128 v[248:251], v219 offset:2368
	s_waitcnt lgkmcnt(6)
	v_mfma_f32_16x16x32_bf16 v[194:197], v[194:197], v[72:75], 0
	s_waitcnt lgkmcnt(5)
	v_mfma_f32_16x16x32_bf16 v[232:235], v[232:235], v[72:75], 0
	s_waitcnt lgkmcnt(4)
	v_mfma_f32_16x16x32_bf16 v[244:247], v[244:247], v[72:75], 0
	s_waitcnt lgkmcnt(3)
	v_mfma_f32_16x16x32_bf16 v[236:239], v[236:239], v[72:75], 0
	s_waitcnt lgkmcnt(2)
	v_mfma_f32_16x16x32_bf16 v[194:197], v[198:201], v[68:71], v[194:197]
	ds_read_b128 v[198:201], v219 offset:4672
	s_waitcnt lgkmcnt(2)
	v_mfma_f32_16x16x32_bf16 v[232:235], v[240:243], v[68:71], v[232:235]
	s_waitcnt lgkmcnt(1)
	v_mfma_f32_16x16x32_bf16 v[244:247], v[248:251], v[68:71], v[244:247]
	s_waitcnt lgkmcnt(0)
	v_mfma_f32_16x16x32_bf16 v[236:239], v[198:201], v[68:71], v[236:239]
	v_lshl_add_u64 v[240:241], v[148:149], 0, v[0:1]
	v_lshl_add_u64 v[242:243], v[148:149], 0, v[118:119]
	v_lshl_add_u64 v[248:249], v[148:149], 0, v[120:121]
	v_lshl_add_u64 v[250:251], v[148:149], 0, v[122:123]
	s_nop 3
	v_fma_f32 v194, v96, v104, v194
	v_fma_f32 v195, v97, v105, v195
	v_fma_f32 v196, v98, v106, v196
	v_fma_f32 v197, v99, v107, v197
	v_cvt_pk_bf16_f32 v194, v194, v194
	v_cvt_pk_bf16_f32 v195, v195, v195
	v_cvt_pk_bf16_f32 v196, v196, v196
	v_cvt_pk_bf16_f32 v197, v197, v197
	global_store_short v[240:241], v194, off
	global_store_short v[242:243], v195, off
	global_store_short v[248:249], v196, off
	global_store_short v[250:251], v197, off
	v_lshl_add_u64 v[240:241], v[148:149], 0, v[124:125]
	v_lshl_add_u64 v[242:243], v[148:149], 0, v[126:127]
	v_lshl_add_u64 v[248:249], v[148:149], 0, v[128:129]
	v_lshl_add_u64 v[250:251], v[148:149], 0, v[130:131]
	v_fma_f32 v232, v92, v100, v232
	v_fma_f32 v233, v93, v101, v233
	v_fma_f32 v234, v94, v102, v234
	v_fma_f32 v235, v95, v103, v235
	v_cvt_pk_bf16_f32 v232, v232, v232
	v_cvt_pk_bf16_f32 v233, v233, v233
	v_cvt_pk_bf16_f32 v234, v234, v234
	v_cvt_pk_bf16_f32 v235, v235, v235
	global_store_short v[240:241], v232, off
	global_store_short v[242:243], v233, off
	global_store_short v[248:249], v234, off
	global_store_short v[250:251], v235, off
	v_lshl_add_u64 v[240:241], v[148:149], 0, v[132:133]
	v_lshl_add_u64 v[242:243], v[148:149], 0, v[134:135]
	v_lshl_add_u64 v[248:249], v[148:149], 0, v[136:137]
	v_lshl_add_u64 v[250:251], v[148:149], 0, v[138:139]
	v_fma_f32 v244, v80, v88, v244
	v_fma_f32 v245, v81, v89, v245
	v_fma_f32 v246, v82, v90, v246
	v_fma_f32 v247, v83, v91, v247
	v_cvt_pk_bf16_f32 v244, v244, v244
	v_cvt_pk_bf16_f32 v245, v245, v245
	v_cvt_pk_bf16_f32 v246, v246, v246
	v_cvt_pk_bf16_f32 v247, v247, v247
	global_store_short v[240:241], v244, off
	global_store_short v[242:243], v245, off
	global_store_short v[248:249], v246, off
	global_store_short v[250:251], v247, off
	v_lshl_add_u64 v[240:241], v[148:149], 0, v[140:141]
	v_lshl_add_u64 v[242:243], v[148:149], 0, v[142:143]
	v_lshl_add_u64 v[248:249], v[148:149], 0, v[144:145]
	v_lshl_add_u64 v[250:251], v[148:149], 0, v[146:147]
	v_fma_f32 v236, v76, v84, v236
	v_fma_f32 v237, v77, v85, v237
	v_fma_f32 v238, v78, v86, v238
	v_fma_f32 v239, v79, v87, v239
	v_cvt_pk_bf16_f32 v236, v236, v236
	v_cvt_pk_bf16_f32 v237, v237, v237
	v_cvt_pk_bf16_f32 v238, v238, v238
	v_cvt_pk_bf16_f32 v239, v239, v239
	global_store_short v[240:241], v236, off
	global_store_short v[242:243], v237, off
	global_store_short v[248:249], v238, off
	global_store_short v[250:251], v239, off
	v_mov_b32_e32 v76, s17
	ds_read_b32 v76, v76
	v_add_u32_e32 v83, v161, v155
	v_add_u32_e32 v82, v181, v182
	v_add_u32_e32 v84, v161, v182
	v_add_u32_e32 v85, v161, v183
	v_add_u32_e32 v86, v161, v162
	ds_read_b128 v[88:91], v83 offset:34816
	ds_read_b128 v[92:95], v82 offset:34816
	ds_read_b128 v[96:99], v190 offset:34816
	ds_read_b128 v[100:103], v191 offset:34816
	ds_read_b128 v[104:107], v83 offset:44096
	ds_read_b128 v[194:197], v84 offset:46400
	ds_read_b128 v[198:201], v85 offset:48704
	ds_read_b128 v[232:235], v86 offset:51008
	s_waitcnt lgkmcnt(8)
; #define LAS __attribute__((address_space(3)))
; #define MFMA16(a, b, c) __builtin_amdgcn_mfma_f32_16x16x32_bf16((a), (b), (c), 0, 0, 0)
; template <int MODE>
; __device__ NOINL void chain_item(const LAS Params* lp, int l, int item, bool ctx_out, LAS unsigned char* lds) {
;     ...
;         {
;             const float gl = MODE == 0 ? gcs[128 + 63] : __expf(64.f * lg);
; #pragma unroll
;             for (int dk = 0; dk < NDK; ++dk) {
;                 Sacc[dk] = Sacc[dk] * gl;
; #pragma unroll
;                 for (int ks = 0; ks < 2; ++ks) { const bf16x8 A = *(const LAS bf16x8*)(KT + (kcol + 16 * dk + fr) * 72 + (((ks * 4 + fq) ^ (((kcol >> 4) + dk) & 7)) << 3)); Sacc[dk] = MFMA16(A, Bv[ks], Sacc[dk]); }
;             }
;         }
;     }
	v_pk_mul_f32 v[30:31], v[30:31], v[76:77] op_sel_hi:[1,0]
	v_pk_mul_f32 v[28:29], v[28:29], v[76:77] op_sel_hi:[1,0]
	v_pk_mul_f32 v[42:43], v[42:43], v[76:77] op_sel_hi:[1,0]
	v_pk_mul_f32 v[40:41], v[40:41], v[76:77] op_sel_hi:[1,0]
	v_pk_mul_f32 v[34:35], v[34:35], v[76:77] op_sel_hi:[1,0]
	v_pk_mul_f32 v[32:33], v[32:33], v[76:77] op_sel_hi:[1,0]
	v_pk_mul_f32 v[38:39], v[38:39], v[76:77] op_sel_hi:[1,0]
	v_pk_mul_f32 v[36:37], v[36:37], v[76:77] op_sel_hi:[1,0]
	v_pk_mul_f32 v[58:59], v[58:59], v[76:77] op_sel_hi:[1,0]
	v_pk_mul_f32 v[56:57], v[56:57], v[76:77] op_sel_hi:[1,0]
	v_pk_mul_f32 v[54:55], v[54:55], v[76:77] op_sel_hi:[1,0]
	v_pk_mul_f32 v[52:53], v[52:53], v[76:77] op_sel_hi:[1,0]
	v_pk_mul_f32 v[46:47], v[46:47], v[76:77] op_sel_hi:[1,0]
	v_pk_mul_f32 v[44:45], v[44:45], v[76:77] op_sel_hi:[1,0]
	v_pk_mul_f32 v[50:51], v[50:51], v[76:77] op_sel_hi:[1,0]
	v_pk_mul_f32 v[48:49], v[48:49], v[76:77] op_sel_hi:[1,0]
	s_waitcnt lgkmcnt(7)
	v_mfma_f32_16x16x32_bf16 v[28:31], v[88:91], v[72:75], v[28:31]
	ds_read_b128 v[88:91], v83 offset:34880
	s_waitcnt lgkmcnt(7)
	v_mfma_f32_16x16x32_bf16 v[40:43], v[92:95], v[72:75], v[40:43]
	ds_read_b128 v[92:95], v82 offset:34880
	s_waitcnt lgkmcnt(7)
	v_mfma_f32_16x16x32_bf16 v[32:35], v[96:99], v[72:75], v[32:35]
	ds_read_b128 v[96:99], v190 offset:34880
	s_waitcnt lgkmcnt(7)
	v_mfma_f32_16x16x32_bf16 v[36:39], v[100:103], v[72:75], v[36:39]
	ds_read_b128 v[100:103], v191 offset:34880
	s_waitcnt lgkmcnt(7)
	v_mfma_f32_16x16x32_bf16 v[56:59], v[104:107], v[72:75], v[56:59]
	ds_read_b128 v[104:107], v83 offset:44032
	s_waitcnt lgkmcnt(7)
	v_mfma_f32_16x16x32_bf16 v[52:55], v[194:197], v[72:75], v[52:55]
	ds_read_b128 v[194:197], v84 offset:46336
	s_waitcnt lgkmcnt(7)
	v_mfma_f32_16x16x32_bf16 v[44:47], v[198:201], v[72:75], v[44:47]
	ds_read_b128 v[198:201], v85 offset:48640
	s_waitcnt lgkmcnt(7)
	v_mfma_f32_16x16x32_bf16 v[48:51], v[232:235], v[72:75], v[48:51]
	ds_read_b128 v[232:235], v86 offset:50944
	s_waitcnt lgkmcnt(7)
	v_mfma_f32_16x16x32_bf16 v[28:31], v[88:91], v[68:71], v[28:31]
	s_waitcnt lgkmcnt(6)
	v_mfma_f32_16x16x32_bf16 v[40:43], v[92:95], v[68:71], v[40:43]
	s_waitcnt lgkmcnt(5)
	v_mfma_f32_16x16x32_bf16 v[32:35], v[96:99], v[68:71], v[32:35]
	s_waitcnt lgkmcnt(4)
	v_mfma_f32_16x16x32_bf16 v[36:39], v[100:103], v[68:71], v[36:39]
	s_waitcnt lgkmcnt(3)
	v_mfma_f32_16x16x32_bf16 v[56:59], v[104:107], v[68:71], v[56:59]
	s_waitcnt lgkmcnt(2)
	v_mfma_f32_16x16x32_bf16 v[52:55], v[194:197], v[68:71], v[52:55]
	s_waitcnt lgkmcnt(1)
	v_mfma_f32_16x16x32_bf16 v[44:47], v[198:201], v[68:71], v[44:47]
	s_waitcnt lgkmcnt(0)
	v_mfma_f32_16x16x32_bf16 v[48:51], v[232:235], v[68:71], v[48:51]
	s_waitcnt vmcnt(19)
	v_mov_b64_e32 v[74:75], v[66:67]
	v_mov_b64_e32 v[70:71], v[62:63]
	v_mov_b64_e32 v[72:73], v[64:65]
	v_mov_b64_e32 v[68:69], v[60:61]
	s_cbranch_scc0 .LBB0_1135
	.p2align	6
